# attention loops: barrier moved 2 MFMAs earlier and next-tile LDS-DMA interleaved with last PV MFMAs, no static setprio; mem-attention QK LDS reads pipelined; bit-identical output
# baseline (speedup 1.0000x reference)
; #define SBAR() __builtin_amdgcn_sched_barrier(0)
; #define LGKM_WAIT8() do { asm volatile("s_waitcnt lgkmcnt(8)" ::: "memory"); SBAR(); } while (0)
; #define EX4(P, B) do { _Pragma("unroll") for (int r_ = (B); r_ < (B) + 4; ++r_) { P[r_] = __builtin_amdgcn_exp2f(fmaf(P[r_], C, mnC)); ps += P[r_]; } } while (0)
; __device__ __forceinline__ void exp_pv256(f32x16 (&o)[8], f32x16& p0, f32x16& p1, int vb, float C, float mnC, float& ps) {
;   VG4 fa, fb; bf16x8 pa, pn;
;   ps = 0.f;
;   EX4(p0, 0); EX4(p0, 4); pa = pk4<0>(p0);
;   asm volatile("s_waitcnt lgkmcnt(0)" ::: "memory"); SBAR();
;   vg4_read<0>(fa, vb); vg4_read<0>(fb, vb + 16384);
;   LGKM_WAIT8(); vg4_mma<0>(o, fa, pa); EX4(p0, 8); SBAR();
;   vg4_read<1>(fa, vb); LGKM_WAIT8(); vg4_mma<1>(o, fb, pa); EX4(p0, 12); pn = pk4<8>(p0); SBAR();
;   vg4_read<1>(fb, vb + 16384); LGKM_WAIT8(); vg4_mma<0>(o, fa, pn); EX4(p1, 0); SBAR();
;   vg4_read<2>(fa, vb); LGKM_WAIT8(); vg4_mma<1>(o, fb, pn); EX4(p1, 4); pa = pk4<0>(p1); SBAR();
;   vg4_read<2>(fb, vb + 16384); LGKM_WAIT8(); vg4_mma<0>(o, fa, pa); EX4(p1, 8); SBAR();
;   vg4_read<3>(fa, vb); LGKM_WAIT8(); vg4_mma<1>(o, fb, pa); EX4(p1, 12); pn = pk4<8>(p1); SBAR();
;   vg4_read<3>(fb, vb + 16384); LGKM_WAIT8(); vg4_mma<0>(o, fa, pn); SBAR();
.LBB0_668:
	v_mul_f32_e32 v14, 0xbe0293ee, v238
	v_fmamk_f32 v2, v160, 0x3e0293ee, v14
	v_exp_f32_e32 v2, v2
	v_fmamk_f32 v3, v161, 0x3e0293ee, v14
	v_exp_f32_e32 v3, v3
	v_fmamk_f32 v4, v162, 0x3e0293ee, v14
	v_exp_f32_e32 v4, v4
	v_fmamk_f32 v5, v163, 0x3e0293ee, v14
	v_exp_f32_e32 v5, v5
	v_fmamk_f32 v7, v164, 0x3e0293ee, v14
	v_add_f32_e32 v6, 0, v2
	v_exp_f32_e32 v7, v7
	v_fmamk_f32 v8, v165, 0x3e0293ee, v14
	v_add_f32_e32 v6, v3, v6
	v_exp_f32_e32 v8, v8
	v_fmamk_f32 v9, v166, 0x3e0293ee, v14
	v_add_f32_e32 v6, v4, v6
	v_exp_f32_e32 v9, v9
	v_fmamk_f32 v10, v167, 0x3e0293ee, v14
	v_add_f32_e32 v6, v5, v6
	v_exp_f32_e32 v10, v10
	v_add_f32_e32 v6, v7, v6
	v_cvt_pk_bf16_f32 v2, v2, v3
	v_cvt_pk_bf16_f32 v3, v4, v5
	v_cvt_pk_bf16_f32 v4, v7, v8
	v_cvt_pk_bf16_f32 v5, v9, v10
	s_waitcnt lgkmcnt(0)
	v_add_f32_e32 v6, v8, v6
	s_add_i32 s45, s45, 1
	v_add_f32_e32 v6, v9, v6
	v_permlane32_swap_b32_e32 v2, v4
	v_add_u32_e32 v15, s4, v237
	v_add_f32_e32 v248, v10, v6
	v_permlane32_swap_b32_e32 v3, v5
	ds_read_b64_tr_b16 v[6:7], v15 offset:0
	ds_read_b64_tr_b16 v[8:9], v15 offset:0x800
	ds_read_b64_tr_b16 v[10:11], v15 offset:0x200
	ds_read_b64_tr_b16 v[12:13], v15 offset:0xa00
	ds_read_b64_tr_b16 v[160:161], v15 offset:0x400
	ds_read_b64_tr_b16 v[162:163], v15 offset:0xc00
	ds_read_b64_tr_b16 v[164:165], v15 offset:0x600
	ds_read_b64_tr_b16 v[166:167], v15 offset:0xe00
	v_add_u32_e32 v249, 0x4000, v15
	ds_read_b64_tr_b16 v[208:209], v249 offset:0
	ds_read_b64_tr_b16 v[210:211], v249 offset:0x800
	ds_read_b64_tr_b16 v[212:213], v249 offset:0x200
	ds_read_b64_tr_b16 v[214:215], v249 offset:0xa00
	ds_read_b64_tr_b16 v[240:241], v249 offset:0x400
	ds_read_b64_tr_b16 v[242:243], v249 offset:0xc00
	ds_read_b64_tr_b16 v[244:245], v249 offset:0x600
	ds_read_b64_tr_b16 v[246:247], v249 offset:0xe00
	s_waitcnt lgkmcnt(8)
	s_nop 0
	v_mfma_f32_32x32x16_bf16 v[128:143], v[2:5], v[6:9], v[128:143]
	v_fmamk_f32 v6, v168, 0x3e0293ee, v14
	v_exp_f32_e32 v168, v6
	v_fmamk_f32 v6, v169, 0x3e0293ee, v14
	v_exp_f32_e32 v169, v6
	v_fmamk_f32 v6, v170, 0x3e0293ee, v14
	v_exp_f32_e32 v170, v6
	v_fmamk_f32 v6, v171, 0x3e0293ee, v14
	v_mfma_f32_32x32x16_bf16 v[112:127], v[2:5], v[10:13], v[112:127]
	v_exp_f32_e32 v171, v6
	v_add_f32_e32 v6, v168, v248
	v_add_f32_e32 v6, v169, v6
	v_add_f32_e32 v6, v170, v6
	v_add_f32_e32 v248, v171, v6
	v_mfma_f32_32x32x16_bf16 v[96:111], v[2:5], v[160:163], v[96:111]
	v_mfma_f32_32x32x16_bf16 v[80:95], v[2:5], v[164:167], v[80:95]
	ds_read_b64_tr_b16 v[6:7], v15 offset:0x1000
	ds_read_b64_tr_b16 v[8:9], v15 offset:0x1800
	ds_read_b64_tr_b16 v[10:11], v15 offset:0x1200
	ds_read_b64_tr_b16 v[12:13], v15 offset:0x1a00
	ds_read_b64_tr_b16 v[160:161], v15 offset:0x1400
	ds_read_b64_tr_b16 v[162:163], v15 offset:0x1c00
	ds_read_b64_tr_b16 v[164:165], v15 offset:0x1600
	ds_read_b64_tr_b16 v[166:167], v15 offset:0x1e00
	s_waitcnt lgkmcnt(8)
	v_mfma_f32_32x32x16_bf16 v[64:79], v[2:5], v[208:211], v[64:79]
	v_fmamk_f32 v172, v172, 0x3e0293ee, v14
	v_exp_f32_e32 v172, v172
	v_fmamk_f32 v173, v173, 0x3e0293ee, v14
	v_exp_f32_e32 v173, v173
	v_fmamk_f32 v174, v174, 0x3e0293ee, v14
	v_exp_f32_e32 v174, v174
	v_fmamk_f32 v175, v175, 0x3e0293ee, v14
	v_mfma_f32_32x32x16_bf16 v[48:63], v[2:5], v[212:215], v[48:63]
	v_exp_f32_e32 v175, v175
	v_add_f32_e32 v208, v172, v248
	v_add_f32_e32 v208, v173, v208
	v_add_f32_e32 v208, v174, v208
	v_cvt_pk_bf16_f32 v168, v168, v169
	v_cvt_pk_bf16_f32 v169, v170, v171
	v_cvt_pk_bf16_f32 v170, v172, v173
	v_mfma_f32_32x32x16_bf16 v[32:47], v[2:5], v[240:243], v[32:47]
	v_cvt_pk_bf16_f32 v171, v174, v175
	v_add_f32_e32 v248, v175, v208
	v_permlane32_swap_b32_e32 v168, v170
	v_permlane32_swap_b32_e32 v169, v171
	v_mfma_f32_32x32x16_bf16 v[16:31], v[2:5], v[244:247], v[16:31]
	ds_read_b64_tr_b16 v[2:3], v249 offset:0x1000
	ds_read_b64_tr_b16 v[4:5], v249 offset:0x1800
	ds_read_b64_tr_b16 v[172:173], v249 offset:0x1200
	ds_read_b64_tr_b16 v[174:175], v249 offset:0x1a00
	ds_read_b64_tr_b16 v[208:209], v249 offset:0x1400
	ds_read_b64_tr_b16 v[210:211], v249 offset:0x1c00
	ds_read_b64_tr_b16 v[212:213], v249 offset:0x1600
	ds_read_b64_tr_b16 v[214:215], v249 offset:0x1e00
	s_waitcnt lgkmcnt(8)
	s_nop 0
	v_mfma_f32_32x32x16_bf16 v[128:143], v[168:171], v[6:9], v[128:143]
	v_fmamk_f32 v6, v144, 0x3e0293ee, v14
	v_exp_f32_e32 v240, v6
	v_fmamk_f32 v6, v145, 0x3e0293ee, v14
	v_exp_f32_e32 v241, v6
	v_fmamk_f32 v6, v146, 0x3e0293ee, v14
	v_exp_f32_e32 v242, v6
	v_fmamk_f32 v6, v147, 0x3e0293ee, v14
	v_mfma_f32_32x32x16_bf16 v[112:127], v[168:171], v[10:13], v[112:127]
	v_exp_f32_e32 v243, v6
	v_add_f32_e32 v6, v240, v248
	v_add_f32_e32 v6, v241, v6
	v_add_f32_e32 v6, v242, v6
	v_add_f32_e32 v244, v243, v6
	v_mfma_f32_32x32x16_bf16 v[96:111], v[168:171], v[160:163], v[96:111]
	v_mfma_f32_32x32x16_bf16 v[80:95], v[168:171], v[164:167], v[80:95]
	ds_read_b64_tr_b16 v[6:7], v15 offset:0x2000
	ds_read_b64_tr_b16 v[8:9], v15 offset:0x2800
	ds_read_b64_tr_b16 v[10:11], v15 offset:0x2200
	ds_read_b64_tr_b16 v[12:13], v15 offset:0x2a00
	ds_read_b64_tr_b16 v[144:145], v15 offset:0x2400
	ds_read_b64_tr_b16 v[146:147], v15 offset:0x2c00
	ds_read_b64_tr_b16 v[160:161], v15 offset:0x2600
	ds_read_b64_tr_b16 v[162:163], v15 offset:0x2e00
	s_waitcnt lgkmcnt(8)
; __device__ __forceinline__ void exp_pv256(f32x16 (&o)[8], f32x16& p0, f32x16& p1, int vb, float C, float mnC, float& ps) {
;     ...
;   vg4_read<1>(fb, vb + 16384); LGKM_WAIT8(); vg4_mma<0>(o, fa, pn); EX4(p1, 0); SBAR();
;   vg4_read<2>(fa, vb); LGKM_WAIT8(); vg4_mma<1>(o, fb, pn); EX4(p1, 4); pa = pk4<0>(p1); SBAR();
;   vg4_read<2>(fb, vb + 16384); LGKM_WAIT8(); vg4_mma<0>(o, fa, pa); EX4(p1, 8); SBAR();
;   vg4_read<3>(fa, vb); LGKM_WAIT8(); vg4_mma<1>(o, fb, pa); EX4(p1, 12); pn = pk4<8>(p1); SBAR();
;   vg4_read<3>(fb, vb + 16384); LGKM_WAIT8(); vg4_mma<0>(o, fa, pn); SBAR();
;   LGKM_WAIT0(); vg4_mma<1>(o, fb, pn);
; template <int LD>
; __device__ __forceinline__ void attn256_body(const bf16_t* __restrict__ Qb, const bf16_t* __restrict__ Kh, const unsigned char* __restrict__ Vimg, int seq, char* lds, LAS unsigned char* ldsl,
;                                              f32x16 (&o)[8], float (&rli)[16]) {
;     ...
;   const int NT = seq / 64;
;   const int vb0 = (int)(uintptr_t)lds + 16384 + v_rd_base(lane);
;   const int kbase = (int)(uintptr_t)lds + r32 * 256;
;   constexpr float C = ATT_SCALE * LOG2E;
;   __syncthreads();
;   A2_DMA(0, 0);
;   asm volatile("s_waitcnt vmcnt(0)" ::: "memory"); __syncthreads();
;   if (wid >= 4) __builtin_amdgcn_s_setprio(1);
;   for (int j = 0; j < NT; ++j) {
;     const int cur = j & 1;
;     if (j + 1 < NT) { if (cur) A2_DMA(0, (j + 1) * 64); else A2_DMA(1, (j + 1) * 64); }
;     f32x16 p0 = f32x16{}, p1 = f32x16{}; float pmax;
;     { int ka[4];
; #pragma unroll
;       for (int q = 0; q < 4; ++q) ka[q] = kbase + cur * A2_STAGE + (((2 * q + hi) ^ (r32 & 7)) << 4);
;       pmax = qkt_deep(p0, p1, ka, qr); }
; #pragma unroll
;     for (int r = 0; r < 16; ++r) pmax = fmaxf(pmax, p1[r]);
;     pmax = half_swap_max(pmax);
;     float mn, alpha;
;     if (__builtin_expect(__all(pmax - m_reg <= ATT_THR / ATT_SCALE), 1)) { mn = m_reg; alpha = 1.f; }
;     else { mn = fmaxf(m_reg, pmax); alpha = __builtin_amdgcn_exp2f((m_reg - mn) * C); m_reg = mn; }
;     const float mnC = -mn * C; float ps;
;     if (__any(alpha < 1.f)) { if (hi == 0) al_l[r32] = alpha; asm volatile("s_waitcnt lgkmcnt(0)" ::: "memory");
; #pragma unroll
;       for (int d = 0; d < 8; ++d)
; #pragma unroll
;         for (int r = 0; r < 16; ++r) o[d][r] *= al_l[crow(r, hi)]; }
;     const int vb = vb0 + cur * A2_STAGE;
;     exp_pv256(o, p0, p1, vb, C, mnC, ps);
	v_mfma_f32_32x32x16_bf16 v[64:79], v[168:171], v[2:5], v[64:79]
	v_fmamk_f32 v2, v148, 0x3e0293ee, v14
	v_exp_f32_e32 v4, v2
	v_fmamk_f32 v2, v149, 0x3e0293ee, v14
	v_exp_f32_e32 v5, v2
	v_fmamk_f32 v2, v150, 0x3e0293ee, v14
	v_exp_f32_e32 v148, v2
	v_fmamk_f32 v2, v151, 0x3e0293ee, v14
	v_mfma_f32_32x32x16_bf16 v[48:63], v[168:171], v[172:175], v[48:63]
	v_exp_f32_e32 v149, v2
	v_add_f32_e32 v2, v4, v244
	v_add_f32_e32 v2, v5, v2
	v_add_f32_e32 v2, v148, v2
	v_add_f32_e32 v244, v149, v2
	v_cvt_pk_bf16_f32 v2, v240, v241
	v_cvt_pk_bf16_f32 v3, v242, v243
	v_mfma_f32_32x32x16_bf16 v[32:47], v[168:171], v[208:211], v[32:47]
	v_cvt_pk_bf16_f32 v4, v4, v5
	v_cvt_pk_bf16_f32 v5, v148, v149
	s_nop 0
	v_permlane32_swap_b32_e32 v2, v4
	v_permlane32_swap_b32_e32 v3, v5
	v_mfma_f32_32x32x16_bf16 v[16:31], v[168:171], v[212:215], v[16:31]
	ds_read_b64_tr_b16 v[148:149], v249 offset:0x2000
	ds_read_b64_tr_b16 v[150:151], v249 offset:0x2800
	ds_read_b64_tr_b16 v[164:165], v249 offset:0x2200
	ds_read_b64_tr_b16 v[166:167], v249 offset:0x2a00
	ds_read_b64_tr_b16 v[168:169], v249 offset:0x2400
	ds_read_b64_tr_b16 v[170:171], v249 offset:0x2c00
	ds_read_b64_tr_b16 v[172:173], v249 offset:0x2600
	ds_read_b64_tr_b16 v[174:175], v249 offset:0x2e00
	s_waitcnt lgkmcnt(8)
	s_nop 0
	v_mfma_f32_32x32x16_bf16 v[128:143], v[2:5], v[6:9], v[128:143]
	v_fmamk_f32 v6, v152, 0x3e0293ee, v14
	v_exp_f32_e32 v208, v6
	v_fmamk_f32 v6, v153, 0x3e0293ee, v14
	v_exp_f32_e32 v209, v6
	v_fmamk_f32 v6, v154, 0x3e0293ee, v14
	v_exp_f32_e32 v210, v6
	v_fmamk_f32 v6, v155, 0x3e0293ee, v14
	v_mfma_f32_32x32x16_bf16 v[112:127], v[2:5], v[10:13], v[112:127]
	v_exp_f32_e32 v211, v6
	v_add_f32_e32 v6, v208, v244
	v_add_f32_e32 v6, v209, v6
	v_add_f32_e32 v6, v210, v6
	v_add_f32_e32 v212, v211, v6
	v_mfma_f32_32x32x16_bf16 v[96:111], v[2:5], v[144:147], v[96:111]
	v_mfma_f32_32x32x16_bf16 v[80:95], v[2:5], v[160:163], v[80:95]
	ds_read_b64_tr_b16 v[6:7], v15 offset:0x3000
	ds_read_b64_tr_b16 v[8:9], v15 offset:0x3800
	ds_read_b64_tr_b16 v[10:11], v15 offset:0x3200
	ds_read_b64_tr_b16 v[12:13], v15 offset:0x3a00
	ds_read_b64_tr_b16 v[144:145], v15 offset:0x3400
	ds_read_b64_tr_b16 v[146:147], v15 offset:0x3c00
	ds_read_b64_tr_b16 v[152:153], v15 offset:0x3600
	ds_read_b64_tr_b16 v[154:155], v15 offset:0x3e00
	s_waitcnt lgkmcnt(8)
	v_fmamk_f32 v15, v156, 0x3e0293ee, v14
	v_mfma_f32_32x32x16_bf16 v[64:79], v[2:5], v[148:151], v[64:79]
	v_exp_f32_e32 v15, v15
	v_fmamk_f32 v148, v157, 0x3e0293ee, v14
	v_exp_f32_e32 v150, v148
	v_fmamk_f32 v148, v158, 0x3e0293ee, v14
	v_exp_f32_e32 v151, v148
	v_fmac_f32_e32 v14, 0x3e0293ee, v159
	v_exp_f32_e32 v14, v14
	v_mfma_f32_32x32x16_bf16 v[48:63], v[2:5], v[164:167], v[48:63]
	v_add_f32_e32 v148, v15, v212
	v_add_f32_e32 v148, v150, v148
	v_add_f32_e32 v148, v151, v148
	v_add_f32_e32 v212, v14, v148
	v_cvt_pk_bf16_f32 v148, v208, v209
	v_cvt_pk_bf16_f32 v149, v210, v211
	v_cvt_pk_bf16_f32 v150, v15, v150
	v_mfma_f32_32x32x16_bf16 v[32:47], v[2:5], v[168:171], v[32:47]
	v_cvt_pk_bf16_f32 v151, v151, v14
	v_permlane32_swap_b32_e32 v148, v150
	v_permlane32_swap_b32_e32 v149, v151
	v_mfma_f32_32x32x16_bf16 v[16:31], v[2:5], v[172:175], v[16:31]
	ds_read_b64_tr_b16 v[2:3], v249 offset:0x3000
	ds_read_b64_tr_b16 v[4:5], v249 offset:0x3800
	ds_read_b64_tr_b16 v[156:157], v249 offset:0x3200
	ds_read_b64_tr_b16 v[158:159], v249 offset:0x3a00
	ds_read_b64_tr_b16 v[160:161], v249 offset:0x3400
	ds_read_b64_tr_b16 v[162:163], v249 offset:0x3c00
	ds_read_b64_tr_b16 v[164:165], v249 offset:0x3600
	ds_read_b64_tr_b16 v[166:167], v249 offset:0x3e00
	s_waitcnt lgkmcnt(8)
	s_nop 0
	v_mfma_f32_32x32x16_bf16 v[128:143], v[148:151], v[6:9], v[128:143]
	v_mfma_f32_32x32x16_bf16 v[112:127], v[148:151], v[10:13], v[112:127]
	v_mfma_f32_32x32x16_bf16 v[96:111], v[148:151], v[144:147], v[96:111]
	v_mfma_f32_32x32x16_bf16 v[80:95], v[148:151], v[152:155], v[80:95]
	s_waitcnt lgkmcnt(0)
	s_waitcnt vmcnt(0)
	s_barrier
	v_mfma_f32_32x32x16_bf16 v[64:79], v[148:151], v[2:5], v[64:79]
	v_mov_b32_e32 v2, v212
	s_nop 1
	v_permlane32_swap_b32_e32 v212, v2
	v_add_f32_e32 v2, v212, v2
	v_fmac_f32_e32 v2, v239, v0
	v_lshl_add_u64 v[222:223], v[222:223], 0, s[30:31]
	v_lshl_add_u64 v[224:225], v[224:225], 0, s[26:27]
	v_lshl_add_u64 v[226:227], v[226:227], 0, s[26:27]
	s_cmpk_lt_i32 s45, 0xff
	s_cbranch_scc0 .Ltail_nodma_a
	s_cmp_eq_u32 s4, 0
	v_lshl_add_u64 v[6:7], s[80:81], 0, v[226:227]
	s_cselect_b32 m0, s0, s56
	s_cselect_b32 s5, 0x2000, s89
	v_lshl_add_u64 v[8:9], s[80:81], 0, v[224:225]
	s_cselect_b32 s6, s1, s57
	s_cselect_b32 s7, s28, s60
	s_cselect_b32 s8, s29, s61
	s_cselect_b32 s9, s52, s62
	global_load_lds_dwordx4 v[6:7], off
	s_add_i32 m0, s0, s5
	v_lshl_add_u64 v[6:7], s[80:81], 0, v[222:223]
	global_load_lds_dwordx4 v[8:9], off
	v_mfma_f32_32x32x16_bf16 v[48:63], v[148:151], v[156:159], v[48:63]
	v_lshl_add_u64 v[8:9], v[6:7], 0, s[74:75]
	s_mov_b32 m0, s6
	s_nop 0
	global_load_lds_dwordx4 v[8:9], off
	v_lshl_add_u64 v[8:9], v[6:7], 0, s[14:15]
	s_mov_b32 m0, s7
	s_nop 0
	global_load_lds_dwordx4 v[8:9], off
	v_mfma_f32_32x32x16_bf16 v[32:47], v[148:151], v[160:163], v[32:47]
	v_lshl_add_u64 v[8:9], v[6:7], 0, s[22:23]
	s_mov_b32 m0, s8
	v_lshl_add_u64 v[6:7], v[6:7], 0, s[18:19]
	global_load_lds_dwordx4 v[8:9], off
	s_mov_b32 m0, s9
	s_nop 0
	global_load_lds_dwordx4 v[6:7], off
	v_mfma_f32_32x32x16_bf16 v[16:31], v[148:151], v[164:167], v[16:31]
	s_branch .Ltail_join_a
.Ltail_nodma_a:
	v_mfma_f32_32x32x16_bf16 v[48:63], v[148:151], v[156:159], v[48:63]
	v_mfma_f32_32x32x16_bf16 v[32:47], v[148:151], v[160:163], v[32:47]
	v_mfma_f32_32x32x16_bf16 v[16:31], v[148:151], v[164:167], v[16:31]
.Ltail_join_a:
	s_cmpk_eq_i32 s45, 0x100
	s_cbranch_scc1 .LBB0_671
	v_mov_b32_e32 v239, v2
	s_and_b32 s4, s45, 1
	s_branch .LBB0_663

; #define SBAR() __builtin_amdgcn_sched_barrier(0)
; #define LGKM_WAIT8() do { asm volatile("s_waitcnt lgkmcnt(8)" ::: "memory"); SBAR(); } while (0)
; #define EX4(P, B) do { _Pragma("unroll") for (int r_ = (B); r_ < (B) + 4; ++r_) { P[r_] = __builtin_amdgcn_exp2f(fmaf(P[r_], C, mnC)); ps += P[r_]; } } while (0)
; __device__ __forceinline__ void exp_pv256(f32x16 (&o)[8], f32x16& p0, f32x16& p1, int vb, float C, float mnC, float& ps) {
;   VG4 fa, fb; bf16x8 pa, pn;
;   ps = 0.f;
;   EX4(p0, 0); EX4(p0, 4); pa = pk4<0>(p0);
;   asm volatile("s_waitcnt lgkmcnt(0)" ::: "memory"); SBAR();
;   vg4_read<0>(fa, vb); vg4_read<0>(fb, vb + 16384);
;   LGKM_WAIT8(); vg4_mma<0>(o, fa, pa); EX4(p0, 8); SBAR();
;   vg4_read<1>(fa, vb); LGKM_WAIT8(); vg4_mma<1>(o, fb, pa); EX4(p0, 12); pn = pk4<8>(p0); SBAR();
;   vg4_read<1>(fb, vb + 16384); LGKM_WAIT8(); vg4_mma<0>(o, fa, pn); EX4(p1, 0); SBAR();
;   vg4_read<2>(fa, vb); LGKM_WAIT8(); vg4_mma<1>(o, fb, pn); EX4(p1, 4); pa = pk4<0>(p1); SBAR();
;   vg4_read<2>(fb, vb + 16384); LGKM_WAIT8(); vg4_mma<0>(o, fa, pa); EX4(p1, 8); SBAR();
;   vg4_read<3>(fa, vb); LGKM_WAIT8(); vg4_mma<1>(o, fb, pa); EX4(p1, 12); pn = pk4<8>(p1); SBAR();
;   vg4_read<3>(fb, vb + 16384); LGKM_WAIT8(); vg4_mma<0>(o, fa, pn); SBAR();
.LBB0_682:
	v_mul_f32_e32 v248, 0xbe0293ee, v238
	v_fmamk_f32 v146, v146, 0x3e0293ee, v248
	v_exp_f32_e32 v146, v146
	v_fmamk_f32 v147, v147, 0x3e0293ee, v248
	v_exp_f32_e32 v147, v147
	v_fmamk_f32 v148, v148, 0x3e0293ee, v248
	v_exp_f32_e32 v148, v148
	v_fmamk_f32 v149, v149, 0x3e0293ee, v248
	v_exp_f32_e32 v149, v149
	v_fmamk_f32 v150, v150, 0x3e0293ee, v248
	v_add_f32_e32 v194, 0, v146
	v_exp_f32_e32 v150, v150
	v_fmamk_f32 v151, v151, 0x3e0293ee, v248
	v_add_f32_e32 v194, v147, v194
	v_exp_f32_e32 v151, v151
	v_fmamk_f32 v152, v152, 0x3e0293ee, v248
	v_add_f32_e32 v194, v148, v194
	v_exp_f32_e32 v152, v152
	v_fmamk_f32 v153, v153, 0x3e0293ee, v248
	v_add_f32_e32 v194, v149, v194
	v_exp_f32_e32 v153, v153
	v_add_f32_e32 v194, v150, v194
	v_cvt_pk_bf16_f32 v146, v146, v147
	v_cvt_pk_bf16_f32 v147, v148, v149
	v_cvt_pk_bf16_f32 v148, v150, v151
	v_cvt_pk_bf16_f32 v149, v152, v153
	s_waitcnt lgkmcnt(0)
	v_add_f32_e32 v194, v151, v194
	s_add_i32 s34, s34, 1
	v_add_f32_e32 v194, v152, v194
	v_add_u32_e32 v249, s4, v237
	v_add_f32_e32 v250, v153, v194
	v_permlane32_swap_b32_e32 v146, v148
	v_permlane32_swap_b32_e32 v147, v149
	ds_read_b64_tr_b16 v[150:151], v249 offset:0
	ds_read_b64_tr_b16 v[152:153], v249 offset:0x800
	ds_read_b64_tr_b16 v[194:195], v249 offset:0x200
	ds_read_b64_tr_b16 v[196:197], v249 offset:0xa00
	ds_read_b64_tr_b16 v[198:199], v249 offset:0x400
	ds_read_b64_tr_b16 v[200:201], v249 offset:0xc00
	ds_read_b64_tr_b16 v[202:203], v249 offset:0x600
	ds_read_b64_tr_b16 v[204:205], v249 offset:0xe00
	v_add_u32_e32 v251, 0x4000, v249
	ds_read_b64_tr_b16 v[206:207], v251 offset:0
	ds_read_b64_tr_b16 v[208:209], v251 offset:0x800
	ds_read_b64_tr_b16 v[212:213], v251 offset:0x200
	ds_read_b64_tr_b16 v[214:215], v251 offset:0xa00
	ds_read_b64_tr_b16 v[240:241], v251 offset:0x400
	ds_read_b64_tr_b16 v[242:243], v251 offset:0xc00
	ds_read_b64_tr_b16 v[244:245], v251 offset:0x600
	ds_read_b64_tr_b16 v[246:247], v251 offset:0xe00
	s_waitcnt lgkmcnt(8)
	s_nop 0
	v_mfma_f32_32x32x16_bf16 v[2:17], v[146:149], v[150:153], v[2:17]
	v_fmamk_f32 v150, v154, 0x3e0293ee, v248
	v_exp_f32_e32 v252, v150
	v_fmamk_f32 v150, v155, 0x3e0293ee, v248
	v_exp_f32_e32 v231, v150
	v_fmamk_f32 v150, v156, 0x3e0293ee, v248
	v_exp_f32_e32 v232, v150
	v_fmamk_f32 v150, v157, 0x3e0293ee, v248
	v_mfma_f32_32x32x16_bf16 v[18:33], v[146:149], v[194:197], v[18:33]
	v_exp_f32_e32 v216, v150
	v_add_f32_e32 v150, v252, v250
	v_add_f32_e32 v150, v231, v150
	v_add_f32_e32 v150, v232, v150
	v_add_f32_e32 v217, v216, v150
	v_mfma_f32_32x32x16_bf16 v[34:49], v[146:149], v[198:201], v[34:49]
	v_mfma_f32_32x32x16_bf16 v[50:65], v[146:149], v[202:205], v[50:65]
	ds_read_b64_tr_b16 v[150:151], v249 offset:0x1000
	ds_read_b64_tr_b16 v[152:153], v249 offset:0x1800
	ds_read_b64_tr_b16 v[154:155], v249 offset:0x1200
	ds_read_b64_tr_b16 v[156:157], v249 offset:0x1a00
	ds_read_b64_tr_b16 v[194:195], v249 offset:0x1400
	ds_read_b64_tr_b16 v[196:197], v249 offset:0x1c00
	ds_read_b64_tr_b16 v[198:199], v249 offset:0x1600
	ds_read_b64_tr_b16 v[200:201], v249 offset:0x1e00
	s_waitcnt lgkmcnt(8)
	v_fmamk_f32 v158, v158, 0x3e0293ee, v248
	v_mfma_f32_32x32x16_bf16 v[66:81], v[146:149], v[206:209], v[66:81]
	v_exp_f32_e32 v202, v158
	v_fmamk_f32 v158, v159, 0x3e0293ee, v248
	v_exp_f32_e32 v203, v158
	v_fmamk_f32 v158, v160, 0x3e0293ee, v248
	v_exp_f32_e32 v204, v158
	v_fmamk_f32 v158, v161, 0x3e0293ee, v248
	v_exp_f32_e32 v161, v158
	v_mfma_f32_32x32x16_bf16 v[82:97], v[146:149], v[212:215], v[82:97]
	v_add_f32_e32 v158, v202, v217
	v_add_f32_e32 v158, v203, v158
	v_add_f32_e32 v158, v204, v158
	v_add_f32_e32 v217, v161, v158
	v_cvt_pk_bf16_f32 v158, v252, v231
	v_cvt_pk_bf16_f32 v159, v232, v216
	v_cvt_pk_bf16_f32 v160, v202, v203
	v_mfma_f32_32x32x16_bf16 v[98:113], v[146:149], v[240:243], v[98:113]
	v_cvt_pk_bf16_f32 v161, v204, v161
	v_permlane32_swap_b32_e32 v158, v160
	v_permlane32_swap_b32_e32 v159, v161
	v_mfma_f32_32x32x16_bf16 v[114:129], v[146:149], v[244:247], v[114:129]
	ds_read_b64_tr_b16 v[146:147], v251 offset:0x1000
	ds_read_b64_tr_b16 v[148:149], v251 offset:0x1800
	ds_read_b64_tr_b16 v[202:203], v251 offset:0x1200
	ds_read_b64_tr_b16 v[204:205], v251 offset:0x1a00
	ds_read_b64_tr_b16 v[206:207], v251 offset:0x1400
	ds_read_b64_tr_b16 v[208:209], v251 offset:0x1c00
	ds_read_b64_tr_b16 v[212:213], v251 offset:0x1600
	ds_read_b64_tr_b16 v[214:215], v251 offset:0x1e00
	s_waitcnt lgkmcnt(8)
	s_nop 0
	v_mfma_f32_32x32x16_bf16 v[2:17], v[158:161], v[150:153], v[2:17]
	v_fmamk_f32 v130, v130, 0x3e0293ee, v248
	v_exp_f32_e32 v216, v130
	v_fmamk_f32 v130, v131, 0x3e0293ee, v248
	v_exp_f32_e32 v231, v130
	v_fmamk_f32 v130, v132, 0x3e0293ee, v248
	v_exp_f32_e32 v232, v130
	v_fmamk_f32 v130, v133, 0x3e0293ee, v248
	v_mfma_f32_32x32x16_bf16 v[18:33], v[158:161], v[154:157], v[18:33]
	v_exp_f32_e32 v240, v130
	v_add_f32_e32 v130, v216, v217
	v_add_f32_e32 v130, v231, v130
	v_add_f32_e32 v130, v232, v130
	v_add_f32_e32 v217, v240, v130
	v_mfma_f32_32x32x16_bf16 v[34:49], v[158:161], v[194:197], v[34:49]
	v_mfma_f32_32x32x16_bf16 v[50:65], v[158:161], v[198:201], v[50:65]
	ds_read_b64_tr_b16 v[130:131], v249 offset:0x2000
	ds_read_b64_tr_b16 v[132:133], v249 offset:0x2800
	ds_read_b64_tr_b16 v[150:151], v249 offset:0x2200
	ds_read_b64_tr_b16 v[152:153], v249 offset:0x2a00
	ds_read_b64_tr_b16 v[154:155], v249 offset:0x2400
	ds_read_b64_tr_b16 v[156:157], v249 offset:0x2c00
	ds_read_b64_tr_b16 v[194:195], v249 offset:0x2600
	ds_read_b64_tr_b16 v[196:197], v249 offset:0x2e00
	s_waitcnt lgkmcnt(8)
; __device__ __forceinline__ void exp_pv256(f32x16 (&o)[8], f32x16& p0, f32x16& p1, int vb, float C, float mnC, float& ps) {
;     ...
;   vg4_read<1>(fb, vb + 16384); LGKM_WAIT8(); vg4_mma<0>(o, fa, pn); EX4(p1, 0); SBAR();
;   vg4_read<2>(fa, vb); LGKM_WAIT8(); vg4_mma<1>(o, fb, pn); EX4(p1, 4); pa = pk4<0>(p1); SBAR();
;   vg4_read<2>(fb, vb + 16384); LGKM_WAIT8(); vg4_mma<0>(o, fa, pa); EX4(p1, 8); SBAR();
;   vg4_read<3>(fa, vb); LGKM_WAIT8(); vg4_mma<1>(o, fb, pa); EX4(p1, 12); pn = pk4<8>(p1); SBAR();
;   vg4_read<3>(fb, vb + 16384); LGKM_WAIT8(); vg4_mma<0>(o, fa, pn); SBAR();
;   LGKM_WAIT0(); vg4_mma<1>(o, fb, pn);
; template <int LD>
; __device__ __forceinline__ void attn256_body(const bf16_t* __restrict__ Qb, const bf16_t* __restrict__ Kh, const unsigned char* __restrict__ Vimg, int seq, char* lds, LAS unsigned char* ldsl,
;                                              f32x16 (&o)[8], float (&rli)[16]) {
;     ...
;   const int NT = seq / 64;
;   const int vb0 = (int)(uintptr_t)lds + 16384 + v_rd_base(lane);
;   const int kbase = (int)(uintptr_t)lds + r32 * 256;
;   constexpr float C = ATT_SCALE * LOG2E;
;   __syncthreads();
;   A2_DMA(0, 0);
;   asm volatile("s_waitcnt vmcnt(0)" ::: "memory"); __syncthreads();
;   if (wid >= 4) __builtin_amdgcn_s_setprio(1);
;   for (int j = 0; j < NT; ++j) {
;     const int cur = j & 1;
;     if (j + 1 < NT) { if (cur) A2_DMA(0, (j + 1) * 64); else A2_DMA(1, (j + 1) * 64); }
;     f32x16 p0 = f32x16{}, p1 = f32x16{}; float pmax;
;     { int ka[4];
; #pragma unroll
;       for (int q = 0; q < 4; ++q) ka[q] = kbase + cur * A2_STAGE + (((2 * q + hi) ^ (r32 & 7)) << 4);
;       pmax = qkt_deep(p0, p1, ka, qr); }
; #pragma unroll
;     for (int r = 0; r < 16; ++r) pmax = fmaxf(pmax, p1[r]);
;     pmax = half_swap_max(pmax);
;     float mn, alpha;
;     if (__builtin_expect(__all(pmax - m_reg <= ATT_THR / ATT_SCALE), 1)) { mn = m_reg; alpha = 1.f; }
;     else { mn = fmaxf(m_reg, pmax); alpha = __builtin_amdgcn_exp2f((m_reg - mn) * C); m_reg = mn; }
;     const float mnC = -mn * C; float ps;
;     if (__any(alpha < 1.f)) { if (hi == 0) al_l[r32] = alpha; asm volatile("s_waitcnt lgkmcnt(0)" ::: "memory");
; #pragma unroll
;       for (int d = 0; d < 8; ++d)
; #pragma unroll
;         for (int r = 0; r < 16; ++r) o[d][r] *= al_l[crow(r, hi)]; }
;     const int vb = vb0 + cur * A2_STAGE;
;     exp_pv256(o, p0, p1, vb, C, mnC, ps);
	v_fmamk_f32 v134, v134, 0x3e0293ee, v248
	v_mfma_f32_32x32x16_bf16 v[66:81], v[158:161], v[146:149], v[66:81]
	v_exp_f32_e32 v146, v134
	v_fmamk_f32 v134, v135, 0x3e0293ee, v248
	v_exp_f32_e32 v147, v134
	v_fmamk_f32 v134, v136, 0x3e0293ee, v248
	v_exp_f32_e32 v148, v134
	v_fmamk_f32 v134, v137, 0x3e0293ee, v248
	v_exp_f32_e32 v137, v134
	v_mfma_f32_32x32x16_bf16 v[82:97], v[158:161], v[202:205], v[82:97]
	v_add_f32_e32 v134, v146, v217
	v_add_f32_e32 v134, v147, v134
	v_add_f32_e32 v134, v148, v134
	v_add_f32_e32 v217, v137, v134
	v_cvt_pk_bf16_f32 v134, v216, v231
	v_cvt_pk_bf16_f32 v135, v232, v240
	v_cvt_pk_bf16_f32 v136, v146, v147
	v_mfma_f32_32x32x16_bf16 v[98:113], v[158:161], v[206:209], v[98:113]
	v_cvt_pk_bf16_f32 v137, v148, v137
	v_permlane32_swap_b32_e32 v134, v136
	v_permlane32_swap_b32_e32 v135, v137
	v_mfma_f32_32x32x16_bf16 v[114:129], v[158:161], v[212:215], v[114:129]
	ds_read_b64_tr_b16 v[146:147], v251 offset:0x2000
	ds_read_b64_tr_b16 v[148:149], v251 offset:0x2800
	ds_read_b64_tr_b16 v[158:159], v251 offset:0x2200
	ds_read_b64_tr_b16 v[160:161], v251 offset:0x2a00
	ds_read_b64_tr_b16 v[198:199], v251 offset:0x2400
	ds_read_b64_tr_b16 v[200:201], v251 offset:0x2c00
	ds_read_b64_tr_b16 v[202:203], v251 offset:0x2600
	ds_read_b64_tr_b16 v[204:205], v251 offset:0x2e00
	s_waitcnt lgkmcnt(8)
	s_nop 0
	v_mfma_f32_32x32x16_bf16 v[2:17], v[134:137], v[130:133], v[2:17]
	v_fmamk_f32 v130, v138, 0x3e0293ee, v248
	v_exp_f32_e32 v206, v130
	v_fmamk_f32 v130, v139, 0x3e0293ee, v248
	v_exp_f32_e32 v207, v130
	v_fmamk_f32 v130, v140, 0x3e0293ee, v248
	v_exp_f32_e32 v208, v130
	v_fmamk_f32 v130, v141, 0x3e0293ee, v248
	v_mfma_f32_32x32x16_bf16 v[18:33], v[134:137], v[150:153], v[18:33]
	v_exp_f32_e32 v209, v130
	v_add_f32_e32 v130, v206, v217
	v_add_f32_e32 v130, v207, v130
	v_add_f32_e32 v130, v208, v130
	v_add_f32_e32 v212, v209, v130
	v_mfma_f32_32x32x16_bf16 v[34:49], v[134:137], v[154:157], v[34:49]
	v_mfma_f32_32x32x16_bf16 v[50:65], v[134:137], v[194:197], v[50:65]
	ds_read_b64_tr_b16 v[130:131], v249 offset:0x3000
	ds_read_b64_tr_b16 v[132:133], v249 offset:0x3800
	ds_read_b64_tr_b16 v[138:139], v249 offset:0x3200
	ds_read_b64_tr_b16 v[140:141], v249 offset:0x3a00
	ds_read_b64_tr_b16 v[150:151], v249 offset:0x3400
	ds_read_b64_tr_b16 v[152:153], v249 offset:0x3c00
	ds_read_b64_tr_b16 v[154:155], v249 offset:0x3600
	ds_read_b64_tr_b16 v[156:157], v249 offset:0x3e00
	s_waitcnt lgkmcnt(8)
	v_fmamk_f32 v142, v142, 0x3e0293ee, v248
	v_mfma_f32_32x32x16_bf16 v[66:81], v[134:137], v[146:149], v[66:81]
	v_exp_f32_e32 v146, v142
	v_fmamk_f32 v142, v143, 0x3e0293ee, v248
	v_exp_f32_e32 v147, v142
	v_fmamk_f32 v142, v144, 0x3e0293ee, v248
	v_exp_f32_e32 v148, v142
	v_fmac_f32_e32 v248, 0x3e0293ee, v145
	v_exp_f32_e32 v145, v248
	v_mfma_f32_32x32x16_bf16 v[82:97], v[134:137], v[158:161], v[82:97]
	v_add_f32_e32 v142, v146, v212
	v_add_f32_e32 v142, v147, v142
	v_add_f32_e32 v142, v148, v142
	v_add_f32_e32 v212, v145, v142
	v_cvt_pk_bf16_f32 v142, v206, v207
	v_cvt_pk_bf16_f32 v143, v208, v209
	v_cvt_pk_bf16_f32 v144, v146, v147
	v_mfma_f32_32x32x16_bf16 v[98:113], v[134:137], v[198:201], v[98:113]
	v_cvt_pk_bf16_f32 v145, v148, v145
	v_permlane32_swap_b32_e32 v142, v144
	v_permlane32_swap_b32_e32 v143, v145
	v_mfma_f32_32x32x16_bf16 v[114:129], v[134:137], v[202:205], v[114:129]
	ds_read_b64_tr_b16 v[134:135], v251 offset:0x3000
	ds_read_b64_tr_b16 v[136:137], v251 offset:0x3800
	ds_read_b64_tr_b16 v[146:147], v251 offset:0x3200
	ds_read_b64_tr_b16 v[148:149], v251 offset:0x3a00
	ds_read_b64_tr_b16 v[158:159], v251 offset:0x3400
	ds_read_b64_tr_b16 v[160:161], v251 offset:0x3c00
	ds_read_b64_tr_b16 v[194:195], v251 offset:0x3600
	ds_read_b64_tr_b16 v[196:197], v251 offset:0x3e00
	s_waitcnt lgkmcnt(8)
	s_nop 0
	v_mfma_f32_32x32x16_bf16 v[2:17], v[142:145], v[130:133], v[2:17]
	v_mfma_f32_32x32x16_bf16 v[18:33], v[142:145], v[138:141], v[18:33]
	v_mfma_f32_32x32x16_bf16 v[34:49], v[142:145], v[150:153], v[34:49]
	v_mfma_f32_32x32x16_bf16 v[50:65], v[142:145], v[154:157], v[50:65]
	s_waitcnt lgkmcnt(0)
	s_waitcnt vmcnt(0)
	s_barrier
	v_mfma_f32_32x32x16_bf16 v[66:81], v[142:145], v[134:137], v[66:81]
	v_mov_b32_e32 v130, v212
	s_nop 1
	v_permlane32_swap_b32_e32 v212, v130
	v_add_f32_e32 v130, v212, v130
	v_fmac_f32_e32 v130, v239, v0
	v_lshl_add_u64 v[222:223], v[222:223], 0, s[30:31]
	v_lshl_add_u64 v[224:225], v[224:225], 0, s[26:27]
	v_lshl_add_u64 v[226:227], v[226:227], 0, s[26:27]
	s_cmpk_lt_i32 s34, 0xff
	s_cbranch_scc0 .Ltail_nodma_b
	s_cmp_eq_u32 s4, 0
	v_lshl_add_u64 v[138:139], s[80:81], 0, v[224:225]
	s_cselect_b32 m0, s0, s35
	s_cselect_b32 s5, 0x2000, s89
	v_lshl_add_u64 v[140:141], s[80:81], 0, v[226:227]
	s_cselect_b32 s6, s1, s44
	s_cselect_b32 s7, s24, s45
	s_cselect_b32 s8, s25, s48
	s_cselect_b32 s9, s28, s49
	global_load_lds_dwordx4 v[138:139], off
	s_add_i32 m0, s0, s5
	v_lshl_add_u64 v[138:139], s[80:81], 0, v[222:223]
	global_load_lds_dwordx4 v[140:141], off
	v_mfma_f32_32x32x16_bf16 v[82:97], v[142:145], v[146:149], v[82:97]
	v_lshl_add_u64 v[140:141], v[138:139], 0, s[74:75]
	s_mov_b32 m0, s6
	s_nop 0
	global_load_lds_dwordx4 v[140:141], off
	v_lshl_add_u64 v[140:141], v[138:139], 0, s[14:15]
	s_mov_b32 m0, s7
	s_nop 0
	global_load_lds_dwordx4 v[140:141], off
	v_mfma_f32_32x32x16_bf16 v[98:113], v[142:145], v[158:161], v[98:113]
	v_lshl_add_u64 v[140:141], v[138:139], 0, s[22:23]
	s_mov_b32 m0, s8
	v_lshl_add_u64 v[138:139], v[138:139], 0, s[18:19]
	global_load_lds_dwordx4 v[140:141], off
	s_mov_b32 m0, s9
	s_nop 0
	global_load_lds_dwordx4 v[138:139], off
	v_mfma_f32_32x32x16_bf16 v[114:129], v[142:145], v[194:197], v[114:129]
	s_branch .Ltail_join_b
.Ltail_nodma_b:
	v_mfma_f32_32x32x16_bf16 v[82:97], v[142:145], v[146:149], v[82:97]
	v_mfma_f32_32x32x16_bf16 v[98:113], v[142:145], v[158:161], v[98:113]
	v_mfma_f32_32x32x16_bf16 v[114:129], v[142:145], v[194:197], v[114:129]
.Ltail_join_b:
	s_cmpk_eq_i32 s34, 0x100
	s_cbranch_scc1 .LBB0_685
	v_mov_b32_e32 v239, v130
	s_and_b32 s4, s34, 1
	s_branch .LBB0_677
